# v10 plus one s_nop before the attention tile loop: shifts attention and later code by 4 bytes (code placement parity as baseline)
# speedup vs baseline: 1.0035x; 1.0035x over previous
.LBB0_339:
	s_lshl_b32 s70, s6, 2
	s_ashr_i32 s71, s68, 7
	s_add_i32 s63, s70, 4
	s_add_i32 s72, s71, s70
	v_mov_b32_e32 v145, 0
	s_cmp_lt_i32 s72, 0
	v_mov_b32_e32 v144, 0
	v_mov_b32_e32 v143, 0
	v_mov_b32_e32 v142, 0
	v_mov_b32_e32 v141, 0
	v_mov_b32_e32 v140, 0
	v_mov_b32_e32 v139, 0
	v_mov_b32_e32 v138, 0
	v_mov_b32_e32 v137, 0
	v_mov_b32_e32 v136, 0
	v_mov_b32_e32 v135, 0
	v_mov_b32_e32 v134, 0
	v_mov_b32_e32 v133, 0
	v_mov_b32_e32 v132, 0
	v_mov_b32_e32 v131, 0
	v_mov_b32_e32 v130, 0
	v_mov_b32_e32 v129, 0
	v_mov_b32_e32 v128, 0
	v_mov_b32_e32 v127, 0
	v_mov_b32_e32 v126, 0
	v_mov_b32_e32 v125, 0
	v_mov_b32_e32 v124, 0
	v_mov_b32_e32 v123, 0
	v_mov_b32_e32 v122, 0
	v_mov_b32_e32 v121, 0
	v_mov_b32_e32 v120, 0
	v_mov_b32_e32 v119, 0
	v_mov_b32_e32 v118, 0
	v_mov_b32_e32 v117, 0
	v_mov_b32_e32 v116, 0
	v_mov_b32_e32 v115, 0
	v_mov_b32_e32 v114, 0
	v_mov_b32_e32 v113, 0
	v_mov_b32_e32 v112, 0
	v_mov_b32_e32 v111, 0
	v_mov_b32_e32 v110, 0
	v_mov_b32_e32 v109, 0
	v_mov_b32_e32 v108, 0
	v_mov_b32_e32 v107, 0
	v_mov_b32_e32 v106, 0
	v_mov_b32_e32 v105, 0
	v_mov_b32_e32 v104, 0
	v_mov_b32_e32 v103, 0
	v_mov_b32_e32 v102, 0
	v_mov_b32_e32 v101, 0
	v_mov_b32_e32 v100, 0
	v_mov_b32_e32 v99, 0
	v_mov_b32_e32 v98, 0
	v_mov_b32_e32 v97, 0
	v_mov_b32_e32 v96, 0
	v_mov_b32_e32 v95, 0
	v_mov_b32_e32 v94, 0
	v_mov_b32_e32 v93, 0
	v_mov_b32_e32 v92, 0
	v_mov_b32_e32 v91, 0
	v_mov_b32_e32 v90, 0
	v_mov_b32_e32 v89, 0
	v_mov_b32_e32 v88, 0
	v_mov_b32_e32 v87, 0
	v_mov_b32_e32 v86, 0
	v_mov_b32_e32 v85, 0
	v_mov_b32_e32 v84, 0
	v_mov_b32_e32 v83, 0
	v_mov_b32_e32 v82, 0
	v_mov_b32_e32 v81, 0
	v_mov_b32_e32 v80, 0
	v_mov_b32_e32 v79, 0
	v_mov_b32_e32 v78, 0
	v_mov_b32_e32 v77, 0
	v_mov_b32_e32 v76, 0
	v_mov_b32_e32 v75, 0
	v_mov_b32_e32 v74, 0
	v_mov_b32_e32 v73, 0
	v_mov_b32_e32 v72, 0
	v_mov_b32_e32 v71, 0
	v_mov_b32_e32 v70, 0
	v_mov_b32_e32 v69, 0
	v_mov_b32_e32 v68, 0
	v_mov_b32_e32 v67, 0
	v_mov_b32_e32 v66, 0
	v_mov_b32_e32 v65, 0
	v_mov_b32_e32 v64, 0
	v_mov_b32_e32 v63, 0
	v_mov_b32_e32 v62, 0
	v_mov_b32_e32 v61, 0
	v_mov_b32_e32 v60, 0
	v_mov_b32_e32 v59, 0
	v_mov_b32_e32 v58, 0
	v_mov_b32_e32 v57, 0
	v_mov_b32_e32 v56, 0
	v_mov_b32_e32 v55, 0
	v_mov_b32_e32 v54, 0
	v_mov_b32_e32 v53, 0
	v_mov_b32_e32 v52, 0
	v_mov_b32_e32 v51, 0
	v_mov_b32_e32 v50, 0
	v_mov_b32_e32 v49, 0
	v_mov_b32_e32 v48, 0
	v_mov_b32_e32 v47, 0
	v_mov_b32_e32 v46, 0
	v_mov_b32_e32 v45, 0
	v_mov_b32_e32 v44, 0
	v_mov_b32_e32 v43, 0
	v_mov_b32_e32 v42, 0
	v_mov_b32_e32 v41, 0
	v_mov_b32_e32 v40, 0
	v_mov_b32_e32 v39, 0
	v_mov_b32_e32 v38, 0
	v_mov_b32_e32 v37, 0
	v_mov_b32_e32 v36, 0
	v_mov_b32_e32 v35, 0
	v_mov_b32_e32 v34, 0
	v_mov_b32_e32 v33, 0
	v_mov_b32_e32 v32, 0
	v_mov_b32_e32 v31, 0
	v_mov_b32_e32 v30, 0
	v_mov_b32_e32 v29, 0
	v_mov_b32_e32 v28, 0
	v_mov_b32_e32 v27, 0
	v_mov_b32_e32 v26, 0
	v_mov_b32_e32 v25, 0
	v_mov_b32_e32 v24, 0
	v_mov_b32_e32 v23, 0
	v_mov_b32_e32 v22, 0
	v_mov_b32_e32 v21, 0
	v_mov_b32_e32 v20, 0
	v_mov_b32_e32 v19, 0
	v_mov_b32_e32 v18, 0
	v_mov_b32_e32 v16, 0
	s_cbranch_scc1 .LBB0_357
	v_and_b32_e32 v2, 63, v221
	v_lshlrev_b32_e32 v6, 4, v2
	v_lshlrev_b32_e32 v7, 1, v2
	v_lshlrev_b32_e32 v2, 3, v2
	s_lshl_b32 s6, s6, 8
	v_and_b32_e32 v2, 0x118, v2
	s_add_i32 s74, s74, s6
	v_bitop3_b32 v8, v4, v221, 7 bitop3:0x78
	v_and_b32_e32 v6, 0xc0, v6
	v_and_or_b32 v2, v7, 32, v2
	v_lshlrev_b32_e32 v8, 4, v8
	v_lshlrev_b32_e32 v9, 8, v5
	v_add3_u32 v226, v6, s40, v2
	v_mad_i32_i24 v2, v4, -4, s74
	v_mov_b32_e32 v16, v3
	v_mov_b32_e32 v17, v3
	v_or_b32_e32 v222, v8, v9
	v_bitop3_b32 v223, v8, 32, v9 bitop3:0x36
	v_bitop3_b32 v224, v8, 64, v9 bitop3:0x36
	v_bitop3_b32 v225, v8, s33, v9 bitop3:0x36
	v_add3_u32 v227, v2, v5, s35
	v_mov_b32_e32 v2, v3
	v_mov_b32_e32 v4, v3
	v_mov_b32_e32 v5, v3
	v_mov_b32_e32 v6, v3
	v_mov_b32_e32 v7, v3
	v_mov_b32_e32 v8, v3
	v_mov_b32_e32 v9, v3
	v_mov_b32_e32 v10, v3
	v_mov_b32_e32 v11, v3
	v_mov_b32_e32 v12, v3
	v_mov_b32_e32 v13, v3
	v_mov_b32_e32 v14, v3
	v_mov_b32_e32 v15, v3
	v_mov_b64_e32 v[32:33], v[16:17]
	v_mov_b64_e32 v[48:49], v[16:17]
	v_mov_b64_e32 v[64:65], v[16:17]
	v_mov_b64_e32 v[80:81], v[16:17]
	v_mov_b64_e32 v[96:97], v[16:17]
	v_mov_b64_e32 v[112:113], v[16:17]
	v_mov_b64_e32 v[128:129], v[16:17]
	v_mov_b64_e32 v[144:145], v[16:17]
	s_mov_b32 s6, 64
	s_add_i32 s75, s72, 1
	s_mov_b32 s80, 0
	v_mov_b32_e32 v229, 0
	v_mov_b32_e32 v228, 0xf149f2ca
	s_movk_i32 s76, 0x4000
	v_mov_b64_e32 v[30:31], v[14:15]
	v_mov_b64_e32 v[28:29], v[12:13]
	v_mov_b64_e32 v[26:27], v[10:11]
	v_mov_b64_e32 v[24:25], v[8:9]
	v_mov_b64_e32 v[22:23], v[6:7]
	v_mov_b64_e32 v[20:21], v[4:5]
	v_mov_b64_e32 v[18:19], v[2:3]
	v_mov_b64_e32 v[46:47], v[14:15]
	v_mov_b64_e32 v[44:45], v[12:13]
	v_mov_b64_e32 v[42:43], v[10:11]
	v_mov_b64_e32 v[40:41], v[8:9]
	v_mov_b64_e32 v[38:39], v[6:7]
	v_mov_b64_e32 v[36:37], v[4:5]
	v_mov_b64_e32 v[34:35], v[2:3]
	v_mov_b64_e32 v[62:63], v[14:15]
	v_mov_b64_e32 v[60:61], v[12:13]
	v_mov_b64_e32 v[58:59], v[10:11]
	v_mov_b64_e32 v[56:57], v[8:9]
	v_mov_b64_e32 v[54:55], v[6:7]
	v_mov_b64_e32 v[52:53], v[4:5]
	v_mov_b64_e32 v[50:51], v[2:3]
	v_mov_b64_e32 v[78:79], v[14:15]
	v_mov_b64_e32 v[76:77], v[12:13]
	v_mov_b64_e32 v[74:75], v[10:11]
	v_mov_b64_e32 v[72:73], v[8:9]
	v_mov_b64_e32 v[70:71], v[6:7]
	v_mov_b64_e32 v[68:69], v[4:5]
	v_mov_b64_e32 v[66:67], v[2:3]
	v_mov_b64_e32 v[94:95], v[14:15]
	v_mov_b64_e32 v[92:93], v[12:13]
	v_mov_b64_e32 v[90:91], v[10:11]
	v_mov_b64_e32 v[88:89], v[8:9]
	v_mov_b64_e32 v[86:87], v[6:7]
	v_mov_b64_e32 v[84:85], v[4:5]
	v_mov_b64_e32 v[82:83], v[2:3]
	v_mov_b64_e32 v[110:111], v[14:15]
	v_mov_b64_e32 v[108:109], v[12:13]
	v_mov_b64_e32 v[106:107], v[10:11]
	v_mov_b64_e32 v[104:105], v[8:9]
	v_mov_b64_e32 v[102:103], v[6:7]
	v_mov_b64_e32 v[100:101], v[4:5]
	v_mov_b64_e32 v[98:99], v[2:3]
	v_mov_b64_e32 v[126:127], v[14:15]
	v_mov_b64_e32 v[124:125], v[12:13]
	v_mov_b64_e32 v[122:123], v[10:11]
	v_mov_b64_e32 v[120:121], v[8:9]
	v_mov_b64_e32 v[118:119], v[6:7]
	v_mov_b64_e32 v[116:117], v[4:5]
	v_mov_b64_e32 v[114:115], v[2:3]
	v_mov_b64_e32 v[142:143], v[14:15]
	v_mov_b64_e32 v[140:141], v[12:13]
	v_mov_b64_e32 v[138:139], v[10:11]
	v_mov_b64_e32 v[136:137], v[8:9]
	v_mov_b64_e32 v[134:135], v[6:7]
	v_mov_b64_e32 v[132:133], v[4:5]
	v_mov_b64_e32 v[130:131], v[2:3]
	s_mov_b32 s79, 0
	s_waitcnt vmcnt(0)
	s_nop 0
